# up-GEMM unit loop: first K-loop iteration peeled with zero C operands, accumulator zeroing removed
# speedup vs baseline: 1.0078x; 1.0078x over previous
; #define PG8_STAGE(bufoff, gbase, voff) do { _Pragma("unroll") for (int _i = 0; _i < 2; ++_i) \
;         __builtin_amdgcn_global_load_lds((const unsigned*)((const char*)(gbase) + (size_t)_i * r64##voff + voff), (PG8_LAS unsigned*)(lds + (bufoff) + ldsw + _i * 8192), 16, 0, 0); } while (0)
; #define PG8_LDA(dst, b, h) do { _Pragma("unroll") for (int m = 0; m < 4; ++m) _Pragma("unroll") for (int k = 0; k < 2; ++k) dst[m][k] = *(const PG8_LAS bf16x8*)(lds + PG8_SA(b, h) + aoff + m * 2048 + k * 1024); } while (0)
; #define PG8_LDB(dst, b, h) do { _Pragma("unroll") for (int n = 0; n < 2; ++n) _Pragma("unroll") for (int k = 0; k < 2; ++k) dst[n][k] = *(const PG8_LAS bf16x8*)(lds + PG8_SB(b, h) + boff + n * 2048 + k * 1024); } while (0)
; #define PG8_MMA(ai, bj, At, Bt) do { __builtin_amdgcn_s_setprio(1); _Pragma("unroll") for (int m = 0; m < 4; ++m) _Pragma("unroll") for (int n = 0; n < 2; ++n) _Pragma("unroll") for (int k = 0; k < 2; ++k) \
;         acc[ai][bj][m][n] = __builtin_amdgcn_mfma_f32_16x16x32_bf16(Bt[n][k], At[m][k], acc[ai][bj][m][n], 0, 0, 0); __builtin_amdgcn_s_setprio(0); } while (0)
; #define PG8_WAIT_V(n) asm volatile("s_waitcnt vmcnt(" #n ")" ::: "memory")
; template <class Epi, class Sched, bool ALIGN_EPI = false, bool SP2 = false>
; __device__ __forceinline__ void gemm_phase(PG8_LAS unsigned char* lds, const Gemm g, const Sched& S, const Epi& E, int wid0) {
;     ...
;         for (int t = 0; t < nt; t += 2) {
;             const bool last = (t == nt - 2);
;             const char* a1 = cA + (size_t)(t + 1) * kstep;
;             const char* a2 = last ? nA : cA + (size_t)(t + 2) * kstep; const char* b2 = last ? nB : cB + (size_t)(t + 2) * kstep;
;             const char* a3 = a2 + kstep; const char* b3 = b2 + kstep;
;             if (last && has_next) S.a_ready(nxt);
;             if constexpr (SP2) {
;             PG8_LDB(B0, 0, 0); PG8_LDB(B1, 0, 1); PG8_SCHED; PG8_LDA(At, 0, 0); PG8_STAGE(PG8_SA(1, 1), a1 + hstepA, voffA);
;             PG8_WAIT_V(8); PG8_WAIT_L(0); PG8_BAR; PG8_MMA(0, 0, At, B0); PG8_MMA(0, 1, At, B1); PG8_BAR; PG8_SCHED;
;             PG8_LDA(At, 0, 1); PG8_STAGE(PG8_SB(0, 0), b2, voffB); PG8_STAGE(PG8_SB(0, 1), b2 + hstepB, voffB); PG8_STAGE(PG8_SA(0, 0), a2, voffA);
;             PG8_WAIT_V(8); PG8_WAIT_L(0); PG8_BAR; PG8_MMA(1, 0, At, B0); PG8_MMA(1, 1, At, B1); PG8_BAR; PG8_SCHED;
.LBB0_555:
	s_ashr_i32 s45, s44, 31
	s_lshl_b64 s[48:49], s[44:45], 19
	s_add_u32 s48, s23, s48
	s_addc_u32 s49, s16, s49
	s_and_b64 s[4:5], s[4:5], exec
	s_cselect_b32 s45, s49, s47
	s_cselect_b32 vcc_lo, s48, s46
	s_add_u32 s4, s14, 0x40080
	s_addc_u32 s5, s15, 0
	s_add_u32 s46, s46, 0x100
	s_addc_u32 s47, s47, 0
	s_mov_b32 vcc_hi, -2
.Lup_peel:
	s_add_u32 s14, s4, 0xfffc0080
	s_addc_u32 s15, s5, -1
	s_add_i32 s63, 0, 0x10000
	s_cmp_eq_u32 vcc_hi, 12
	s_cselect_b32 s15, s79, s15
	s_cselect_b32 s14, s78, s14
	s_cselect_b32 s95, s45, s47
	s_cselect_b32 s94, vcc_lo, s46
	s_add_i32 s22, 0, 0x14000
	v_add_u32_e32 v142, s63, v1
	v_add_u32_e32 v158, s22, v1
	ds_read_b128 v[102:105], v142
	ds_read_b128 v[134:137], v142 offset:1024
	ds_read_b128 v[138:141], v142 offset:2048
	ds_read_b128 v[142:145], v142 offset:3072
	ds_read_b128 v[146:149], v158
	ds_read_b128 v[150:153], v158 offset:1024
	ds_read_b128 v[154:157], v158 offset:2048
	ds_read_b128 v[158:161], v158 offset:3072
	v_lshl_add_u64 v[194:195], s[4:5], 0, v[206:207]
	s_add_i32 m0, s17, 0xc000
	ds_read_b128 v[162:165], v248
	ds_read_b128 v[166:169], v248 offset:1024
	ds_read_b128 v[170:173], v248 offset:2048
	ds_read_b128 v[174:177], v248 offset:3072
	ds_read_b128 v[178:181], v248 offset:4096
	ds_read_b128 v[182:185], v248 offset:5120
	ds_read_b128 v[186:189], v248 offset:6144
	ds_read_b128 v[190:193], v248 offset:7168
	global_load_lds_dwordx4 v[194:195], off
	v_lshl_add_u64 v[194:195], v[194:195], 0, s[64:65]
	s_add_i32 m0, s17, 0xe000
	s_nop 0
	global_load_lds_dwordx4 v[194:195], off
	s_waitcnt vmcnt(8)
	s_waitcnt lgkmcnt(0)
	s_barrier
	s_setprio 1
	s_waitcnt lgkmcnt(0)
	v_mfma_f32_16x16x32_bf16 v[130:133], v[102:105], v[162:165], 0
	v_mfma_f32_16x16x32_bf16 v[126:129], v[138:141], v[162:165], 0
	v_mfma_f32_16x16x32_bf16 v[122:125], v[102:105], v[170:173], 0
	v_mfma_f32_16x16x32_bf16 v[118:121], v[138:141], v[170:173], 0
	v_mfma_f32_16x16x32_bf16 v[78:81], v[102:105], v[178:181], 0
	v_mfma_f32_16x16x32_bf16 v[86:89], v[138:141], v[178:181], 0
	v_mfma_f32_16x16x32_bf16 v[106:109], v[102:105], v[186:189], 0
	v_mfma_f32_16x16x32_bf16 v[90:93], v[138:141], v[186:189], 0
	v_mfma_f32_16x16x32_bf16 v[130:133], v[134:137], v[166:169], v[130:133]
	v_mfma_f32_16x16x32_bf16 v[126:129], v[142:145], v[166:169], v[126:129]
	v_mfma_f32_16x16x32_bf16 v[122:125], v[134:137], v[174:177], v[122:125]
	v_mfma_f32_16x16x32_bf16 v[118:121], v[142:145], v[174:177], v[118:121]
	v_mfma_f32_16x16x32_bf16 v[78:81], v[134:137], v[182:185], v[78:81]
	v_mfma_f32_16x16x32_bf16 v[86:89], v[142:145], v[182:185], v[86:89]
	v_mfma_f32_16x16x32_bf16 v[106:109], v[134:137], v[190:193], v[106:109]
	v_mfma_f32_16x16x32_bf16 v[90:93], v[142:145], v[190:193], v[90:93]
	s_setprio 0
	s_setprio 1
	v_mfma_f32_16x16x32_bf16 v[114:117], v[146:149], v[162:165], 0
	v_mfma_f32_16x16x32_bf16 v[110:113], v[154:157], v[162:165], 0
	v_mfma_f32_16x16x32_bf16 v[98:101], v[146:149], v[170:173], 0
	v_mfma_f32_16x16x32_bf16 v[94:97], v[154:157], v[170:173], 0
	v_mfma_f32_16x16x32_bf16 v[82:85], v[146:149], v[178:181], 0
	v_mfma_f32_16x16x32_bf16 v[70:73], v[154:157], v[178:181], 0
	v_mfma_f32_16x16x32_bf16 v[74:77], v[146:149], v[186:189], 0
	v_mfma_f32_16x16x32_bf16 v[66:69], v[154:157], v[186:189], 0
	v_mfma_f32_16x16x32_bf16 v[114:117], v[150:153], v[166:169], v[114:117]
	v_mfma_f32_16x16x32_bf16 v[110:113], v[158:161], v[166:169], v[110:113]
	v_mfma_f32_16x16x32_bf16 v[98:101], v[150:153], v[174:177], v[98:101]
	v_mfma_f32_16x16x32_bf16 v[94:97], v[158:161], v[174:177], v[94:97]
	v_mfma_f32_16x16x32_bf16 v[82:85], v[150:153], v[182:185], v[82:85]
	v_mfma_f32_16x16x32_bf16 v[70:73], v[158:161], v[182:185], v[70:73]
	v_mfma_f32_16x16x32_bf16 v[74:77], v[150:153], v[190:193], v[74:77]
	v_mfma_f32_16x16x32_bf16 v[66:69], v[158:161], v[190:193], v[66:69]
	s_setprio 0
	s_barrier
	s_add_i32 s63, s63, s40
	v_lshl_add_u64 v[194:195], s[94:95], 0, v[204:205]
	s_mov_b32 m0, s63
	ds_read_b128 v[162:165], v248 offset:16384
	ds_read_b128 v[166:169], v248 offset:17408
	ds_read_b128 v[170:173], v248 offset:18432
	ds_read_b128 v[174:177], v248 offset:19456
	ds_read_b128 v[178:181], v248 offset:20480
	ds_read_b128 v[182:185], v248 offset:21504
	ds_read_b128 v[186:189], v248 offset:22528
	ds_read_b128 v[190:193], v248 offset:23552
	global_load_lds_dwordx4 v[194:195], off
	v_lshl_add_u64 v[196:197], v[194:195], 0, s[64:65]
	s_add_i32 m0, s63, 0x2000
	s_add_i32 s22, s22, s40
	global_load_lds_dwordx4 v[196:197], off
	v_lshl_add_u64 v[196:197], v[194:195], 0, s[66:67]
	s_mov_b32 m0, s22
	s_nop 0
	global_load_lds_dwordx4 v[196:197], off
	v_lshl_add_u64 v[196:197], v[194:195], 0, s[68:69]
	s_add_i32 m0, s22, 0x2000
	s_nop 0
	global_load_lds_dwordx4 v[196:197], off
	v_lshl_add_u64 v[196:197], s[14:15], 0, v[202:203]
	s_mov_b32 m0, s17
	v_lshl_add_u64 v[198:199], v[196:197], 0, s[64:65]
	global_load_lds_dwordx4 v[196:197], off
	s_mov_b32 m0, s93
	s_nop 0
	global_load_lds_dwordx4 v[198:199], off
	s_waitcnt vmcnt(8)
	s_waitcnt lgkmcnt(0)
	s_barrier
; #define PG8_STAGE(bufoff, gbase, voff) do { _Pragma("unroll") for (int _i = 0; _i < 2; ++_i) \
;         __builtin_amdgcn_global_load_lds((const unsigned*)((const char*)(gbase) + (size_t)_i * r64##voff + voff), (PG8_LAS unsigned*)(lds + (bufoff) + ldsw + _i * 8192), 16, 0, 0); } while (0)
; #define PG8_LDA(dst, b, h) do { _Pragma("unroll") for (int m = 0; m < 4; ++m) _Pragma("unroll") for (int k = 0; k < 2; ++k) dst[m][k] = *(const PG8_LAS bf16x8*)(lds + PG8_SA(b, h) + aoff + m * 2048 + k * 1024); } while (0)
; #define PG8_LDB(dst, b, h) do { _Pragma("unroll") for (int n = 0; n < 2; ++n) _Pragma("unroll") for (int k = 0; k < 2; ++k) dst[n][k] = *(const PG8_LAS bf16x8*)(lds + PG8_SB(b, h) + boff + n * 2048 + k * 1024); } while (0)
; #define PG8_MMA(ai, bj, At, Bt) do { __builtin_amdgcn_s_setprio(1); _Pragma("unroll") for (int m = 0; m < 4; ++m) _Pragma("unroll") for (int n = 0; n < 2; ++n) _Pragma("unroll") for (int k = 0; k < 2; ++k) \
;         acc[ai][bj][m][n] = __builtin_amdgcn_mfma_f32_16x16x32_bf16(Bt[n][k], At[m][k], acc[ai][bj][m][n], 0, 0, 0); __builtin_amdgcn_s_setprio(0); } while (0)
; #define PG8_WAIT_V(n) asm volatile("s_waitcnt vmcnt(" #n ")" ::: "memory")
; #define PG8_WAIT_L(n) asm volatile("s_waitcnt lgkmcnt(" #n ")" ::: "memory")
; #define PG8_BAR __builtin_amdgcn_s_barrier()
; #define PG8_SCHED __builtin_amdgcn_sched_barrier(0)
; template <class Epi, class Sched, bool ALIGN_EPI = false, bool SP2 = false>
; __device__ __forceinline__ void gemm_phase(PG8_LAS unsigned char* lds, const Gemm g, const Sched& S, const Epi& E, int wid0) {
;     ...
;             PG8_WAIT_V(8); PG8_WAIT_L(0); PG8_BAR; PG8_MMA(1, 0, At, B0); PG8_MMA(1, 1, At, B1); PG8_BAR; PG8_SCHED;
;             PG8_LDB(B0, 1, 0); PG8_LDB(B1, 1, 1); PG8_SCHED; PG8_LDA(At, 1, 0); PG8_STAGE(PG8_SA(0, 1), a2 + hstepA, voffA);
;             PG8_WAIT_V(8); PG8_WAIT_L(0); PG8_BAR; PG8_MMA(0, 0, At, B0); PG8_MMA(0, 1, At, B1); PG8_BAR; PG8_SCHED;
	s_setprio 1
	s_waitcnt lgkmcnt(0)
	v_mfma_f32_16x16x32_bf16 v[34:37], v[102:105], v[162:165], 0
	v_mfma_f32_16x16x32_bf16 v[30:33], v[138:141], v[162:165], 0
	v_mfma_f32_16x16x32_bf16 v[22:25], v[102:105], v[170:173], 0
	v_mfma_f32_16x16x32_bf16 v[18:21], v[138:141], v[170:173], 0
	v_mfma_f32_16x16x32_bf16 v[58:61], v[102:105], v[178:181], 0
	v_mfma_f32_16x16x32_bf16 v[50:53], v[138:141], v[178:181], 0
	v_mfma_f32_16x16x32_bf16 v[62:65], v[102:105], v[186:189], 0
	v_mfma_f32_16x16x32_bf16 v[54:57], v[138:141], v[186:189], 0
	v_mfma_f32_16x16x32_bf16 v[34:37], v[134:137], v[166:169], v[34:37]
	v_mfma_f32_16x16x32_bf16 v[30:33], v[142:145], v[166:169], v[30:33]
	v_mfma_f32_16x16x32_bf16 v[22:25], v[134:137], v[174:177], v[22:25]
	v_mfma_f32_16x16x32_bf16 v[18:21], v[142:145], v[174:177], v[18:21]
	v_mfma_f32_16x16x32_bf16 v[58:61], v[134:137], v[182:185], v[58:61]
	v_mfma_f32_16x16x32_bf16 v[50:53], v[142:145], v[182:185], v[50:53]
	v_mfma_f32_16x16x32_bf16 v[62:65], v[134:137], v[190:193], v[62:65]
	v_mfma_f32_16x16x32_bf16 v[54:57], v[142:145], v[190:193], v[54:57]
	s_setprio 0
	s_setprio 1
	v_mfma_f32_16x16x32_bf16 v[14:17], v[146:149], v[162:165], 0
	v_mfma_f32_16x16x32_bf16 v[10:13], v[154:157], v[162:165], 0
	v_mfma_f32_16x16x32_bf16 v[6:9], v[146:149], v[170:173], 0
	v_mfma_f32_16x16x32_bf16 v[2:5], v[154:157], v[170:173], 0
	v_mfma_f32_16x16x32_bf16 v[42:45], v[146:149], v[178:181], 0
	v_mfma_f32_16x16x32_bf16 v[26:29], v[154:157], v[178:181], 0
	v_mfma_f32_16x16x32_bf16 v[46:49], v[146:149], v[186:189], 0
	v_mfma_f32_16x16x32_bf16 v[38:41], v[154:157], v[186:189], 0
	v_mfma_f32_16x16x32_bf16 v[14:17], v[150:153], v[166:169], v[14:17]
	v_mfma_f32_16x16x32_bf16 v[10:13], v[158:161], v[166:169], v[10:13]
	v_mfma_f32_16x16x32_bf16 v[6:9], v[150:153], v[174:177], v[6:9]
	v_mfma_f32_16x16x32_bf16 v[2:5], v[158:161], v[174:177], v[2:5]
	v_mfma_f32_16x16x32_bf16 v[42:45], v[150:153], v[182:185], v[42:45]
	v_mfma_f32_16x16x32_bf16 v[26:29], v[158:161], v[182:185], v[26:29]
	v_mfma_f32_16x16x32_bf16 v[46:49], v[150:153], v[190:193], v[46:49]
	v_mfma_f32_16x16x32_bf16 v[38:41], v[158:161], v[190:193], v[38:41]
	s_setprio 0
	s_barrier
	s_add_i32 s14, 0, 0x18000
	s_add_i32 s15, 0, 0x1c000
	v_add_u32_e32 v142, s14, v1
	v_add_u32_e32 v158, s15, v1
	ds_read_b128 v[102:105], v142
	ds_read_b128 v[134:137], v142 offset:1024
	ds_read_b128 v[138:141], v142 offset:2048
	ds_read_b128 v[142:145], v142 offset:3072
	ds_read_b128 v[146:149], v158
	ds_read_b128 v[150:153], v158 offset:1024
	ds_read_b128 v[154:157], v158 offset:2048
	ds_read_b128 v[158:161], v158 offset:3072
	s_mov_b32 m0, s20
	v_lshl_add_u64 v[198:199], v[196:197], 0, s[66:67]
	ds_read_b128 v[162:165], v248 offset:32768
	ds_read_b128 v[166:169], v248 offset:33792
	ds_read_b128 v[170:173], v248 offset:34816
	ds_read_b128 v[174:177], v248 offset:35840
	ds_read_b128 v[178:181], v248 offset:36864
	ds_read_b128 v[182:185], v248 offset:37888
	ds_read_b128 v[186:189], v248 offset:38912
	ds_read_b128 v[190:193], v248 offset:39936
	global_load_lds_dwordx4 v[198:199], off
	v_lshl_add_u64 v[198:199], v[196:197], 0, s[68:69]
	s_mov_b32 m0, s21
	s_nop 0
	global_load_lds_dwordx4 v[198:199], off
	s_waitcnt vmcnt(8)
	s_waitcnt lgkmcnt(0)
	s_barrier
	s_setprio 1
	s_waitcnt lgkmcnt(0)
	v_mfma_f32_16x16x32_bf16 v[130:133], v[102:105], v[162:165], v[130:133]
	v_mfma_f32_16x16x32_bf16 v[126:129], v[138:141], v[162:165], v[126:129]
	v_mfma_f32_16x16x32_bf16 v[122:125], v[102:105], v[170:173], v[122:125]
	v_mfma_f32_16x16x32_bf16 v[118:121], v[138:141], v[170:173], v[118:121]
	v_mfma_f32_16x16x32_bf16 v[78:81], v[102:105], v[178:181], v[78:81]
	v_mfma_f32_16x16x32_bf16 v[86:89], v[138:141], v[178:181], v[86:89]
	v_mfma_f32_16x16x32_bf16 v[106:109], v[102:105], v[186:189], v[106:109]
	v_mfma_f32_16x16x32_bf16 v[90:93], v[138:141], v[186:189], v[90:93]
	v_mfma_f32_16x16x32_bf16 v[130:133], v[134:137], v[166:169], v[130:133]
	v_mfma_f32_16x16x32_bf16 v[126:129], v[142:145], v[166:169], v[126:129]
	v_mfma_f32_16x16x32_bf16 v[122:125], v[134:137], v[174:177], v[122:125]
	v_mfma_f32_16x16x32_bf16 v[118:121], v[142:145], v[174:177], v[118:121]
	v_mfma_f32_16x16x32_bf16 v[78:81], v[134:137], v[182:185], v[78:81]
	v_mfma_f32_16x16x32_bf16 v[86:89], v[142:145], v[182:185], v[86:89]
	v_mfma_f32_16x16x32_bf16 v[106:109], v[134:137], v[190:193], v[106:109]
	v_mfma_f32_16x16x32_bf16 v[90:93], v[142:145], v[190:193], v[90:93]
	s_setprio 0
	s_setprio 1
	v_mfma_f32_16x16x32_bf16 v[114:117], v[146:149], v[162:165], v[114:117]
	v_mfma_f32_16x16x32_bf16 v[110:113], v[154:157], v[162:165], v[110:113]
	v_mfma_f32_16x16x32_bf16 v[98:101], v[146:149], v[170:173], v[98:101]
	v_mfma_f32_16x16x32_bf16 v[94:97], v[154:157], v[170:173], v[94:97]
	v_mfma_f32_16x16x32_bf16 v[82:85], v[146:149], v[178:181], v[82:85]
	v_mfma_f32_16x16x32_bf16 v[70:73], v[154:157], v[178:181], v[70:73]
	v_mfma_f32_16x16x32_bf16 v[74:77], v[146:149], v[186:189], v[74:77]
	v_mfma_f32_16x16x32_bf16 v[66:69], v[154:157], v[186:189], v[66:69]
	v_mfma_f32_16x16x32_bf16 v[114:117], v[150:153], v[166:169], v[114:117]
	v_mfma_f32_16x16x32_bf16 v[110:113], v[158:161], v[166:169], v[110:113]
	v_mfma_f32_16x16x32_bf16 v[98:101], v[150:153], v[174:177], v[98:101]
	v_mfma_f32_16x16x32_bf16 v[94:97], v[158:161], v[174:177], v[94:97]
	v_mfma_f32_16x16x32_bf16 v[82:85], v[150:153], v[182:185], v[82:85]
	v_mfma_f32_16x16x32_bf16 v[70:73], v[158:161], v[182:185], v[70:73]
	v_mfma_f32_16x16x32_bf16 v[74:77], v[150:153], v[190:193], v[74:77]
	v_mfma_f32_16x16x32_bf16 v[66:69], v[158:161], v[190:193], v[66:69]
	s_setprio 0
	s_barrier
; #define PG8_STAGE(bufoff, gbase, voff) do { _Pragma("unroll") for (int _i = 0; _i < 2; ++_i) \
;         __builtin_amdgcn_global_load_lds((const unsigned*)((const char*)(gbase) + (size_t)_i * r64##voff + voff), (PG8_LAS unsigned*)(lds + (bufoff) + ldsw + _i * 8192), 16, 0, 0); } while (0)
; #define PG8_LDA(dst, b, h) do { _Pragma("unroll") for (int m = 0; m < 4; ++m) _Pragma("unroll") for (int k = 0; k < 2; ++k) dst[m][k] = *(const PG8_LAS bf16x8*)(lds + PG8_SA(b, h) + aoff + m * 2048 + k * 1024); } while (0)
; #define PG8_MMA(ai, bj, At, Bt) do { __builtin_amdgcn_s_setprio(1); _Pragma("unroll") for (int m = 0; m < 4; ++m) _Pragma("unroll") for (int n = 0; n < 2; ++n) _Pragma("unroll") for (int k = 0; k < 2; ++k) \
;         acc[ai][bj][m][n] = __builtin_amdgcn_mfma_f32_16x16x32_bf16(Bt[n][k], At[m][k], acc[ai][bj][m][n], 0, 0, 0); __builtin_amdgcn_s_setprio(0); } while (0)
; #define PG8_WAIT_V(n) asm volatile("s_waitcnt vmcnt(" #n ")" ::: "memory")
; #define PG8_WAIT_L(n) asm volatile("s_waitcnt lgkmcnt(" #n ")" ::: "memory")
; #define PG8_BAR __builtin_amdgcn_s_barrier()
; #define PG8_SCHED __builtin_amdgcn_sched_barrier(0)
; template <class Epi, class Sched, bool ALIGN_EPI = false, bool SP2 = false>
; __device__ __forceinline__ void gemm_phase(PG8_LAS unsigned char* lds, const Gemm g, const Sched& S, const Epi& E, int wid0) {
;     ...
;             PG8_LDA(At, 1, 1); PG8_STAGE(PG8_SB(1, 0), b3, voffB); PG8_STAGE(PG8_SB(1, 1), b3 + hstepB, voffB); PG8_STAGE(PG8_SA(1, 0), a3, voffA);
;             PG8_WAIT_V(8); PG8_WAIT_L(0); PG8_BAR; PG8_MMA(1, 0, At, B0); PG8_MMA(1, 1, At, B1); PG8_BAR; PG8_SCHED;
	s_add_i32 s14, s14, s40
	v_lshl_add_u64 v[198:199], v[194:195], 0, s[70:71]
	s_mov_b32 m0, s14
	ds_read_b128 v[162:165], v248 offset:49152
	ds_read_b128 v[166:169], v248 offset:50176
	ds_read_b128 v[170:173], v248 offset:51200
	ds_read_b128 v[174:177], v248 offset:52224
	ds_read_b128 v[178:181], v248 offset:53248
	ds_read_b128 v[182:185], v248 offset:54272
	ds_read_b128 v[186:189], v248 offset:55296
	ds_read_b128 v[190:193], v248 offset:56320
	global_load_lds_dwordx4 v[198:199], off
	v_lshl_add_u64 v[198:199], v[194:195], 0, s[72:73]
	s_add_i32 m0, s14, 0x2000
	s_add_i32 s14, s15, s40
	global_load_lds_dwordx4 v[198:199], off
	v_lshl_add_u64 v[198:199], v[194:195], 0, s[74:75]
	s_mov_b32 m0, s14
	v_lshl_add_u64 v[194:195], v[194:195], 0, s[76:77]
	global_load_lds_dwordx4 v[198:199], off
	s_add_i32 m0, s14, 0x2000
	s_nop 0
	global_load_lds_dwordx4 v[194:195], off
	v_lshl_add_u64 v[194:195], v[196:197], 0, s[70:71]
	s_mov_b32 m0, s18
	s_nop 0
	global_load_lds_dwordx4 v[194:195], off
	v_lshl_add_u64 v[194:195], v[196:197], 0, s[72:73]
	s_mov_b32 m0, s19
	s_nop 0
	global_load_lds_dwordx4 v[194:195], off
	s_waitcnt vmcnt(8)
	s_waitcnt lgkmcnt(0)
	s_barrier
	s_setprio 1
	s_waitcnt lgkmcnt(0)
	v_mfma_f32_16x16x32_bf16 v[34:37], v[102:105], v[162:165], v[34:37]
	v_mfma_f32_16x16x32_bf16 v[30:33], v[138:141], v[162:165], v[30:33]
	v_mfma_f32_16x16x32_bf16 v[22:25], v[102:105], v[170:173], v[22:25]
	v_mfma_f32_16x16x32_bf16 v[18:21], v[138:141], v[170:173], v[18:21]
	v_mfma_f32_16x16x32_bf16 v[58:61], v[102:105], v[178:181], v[58:61]
	v_mfma_f32_16x16x32_bf16 v[50:53], v[138:141], v[178:181], v[50:53]
	v_mfma_f32_16x16x32_bf16 v[62:65], v[102:105], v[186:189], v[62:65]
	v_mfma_f32_16x16x32_bf16 v[54:57], v[138:141], v[186:189], v[54:57]
	v_mfma_f32_16x16x32_bf16 v[34:37], v[134:137], v[166:169], v[34:37]
	v_mfma_f32_16x16x32_bf16 v[30:33], v[142:145], v[166:169], v[30:33]
	v_mfma_f32_16x16x32_bf16 v[22:25], v[134:137], v[174:177], v[22:25]
	v_mfma_f32_16x16x32_bf16 v[18:21], v[142:145], v[174:177], v[18:21]
	v_mfma_f32_16x16x32_bf16 v[58:61], v[134:137], v[182:185], v[58:61]
	v_mfma_f32_16x16x32_bf16 v[50:53], v[142:145], v[182:185], v[50:53]
	v_mfma_f32_16x16x32_bf16 v[62:65], v[134:137], v[190:193], v[62:65]
	v_mfma_f32_16x16x32_bf16 v[54:57], v[142:145], v[190:193], v[54:57]
	s_setprio 0
	s_setprio 1
	v_mfma_f32_16x16x32_bf16 v[14:17], v[146:149], v[162:165], v[14:17]
	v_mfma_f32_16x16x32_bf16 v[10:13], v[154:157], v[162:165], v[10:13]
	v_mfma_f32_16x16x32_bf16 v[6:9], v[146:149], v[170:173], v[6:9]
	v_mfma_f32_16x16x32_bf16 v[2:5], v[154:157], v[170:173], v[2:5]
	v_mfma_f32_16x16x32_bf16 v[42:45], v[146:149], v[178:181], v[42:45]
	v_mfma_f32_16x16x32_bf16 v[26:29], v[154:157], v[178:181], v[26:29]
	v_mfma_f32_16x16x32_bf16 v[46:49], v[146:149], v[186:189], v[46:49]
	v_mfma_f32_16x16x32_bf16 v[38:41], v[154:157], v[186:189], v[38:41]
	v_mfma_f32_16x16x32_bf16 v[14:17], v[150:153], v[166:169], v[14:17]
	v_mfma_f32_16x16x32_bf16 v[10:13], v[158:161], v[166:169], v[10:13]
	v_mfma_f32_16x16x32_bf16 v[6:9], v[150:153], v[174:177], v[6:9]
	v_mfma_f32_16x16x32_bf16 v[2:5], v[158:161], v[174:177], v[2:5]
	v_mfma_f32_16x16x32_bf16 v[42:45], v[150:153], v[182:185], v[42:45]
	v_mfma_f32_16x16x32_bf16 v[26:29], v[158:161], v[182:185], v[26:29]
	v_mfma_f32_16x16x32_bf16 v[46:49], v[150:153], v[190:193], v[46:49]
	v_mfma_f32_16x16x32_bf16 v[38:41], v[158:161], v[190:193], v[38:41]
	s_setprio 0
	s_barrier
	s_add_i32 vcc_hi, vcc_hi, 2
	s_add_u32 s4, s4, 0x100
	s_addc_u32 s5, s5, 0
	s_add_u32 s46, s46, 0x100
	s_addc_u32 s47, s47, 0
